# S5 scan loop: s_nop kept where the in-loop waits were removed, so VALU->MFMA and MFMA->permlane wait-state distances equal the compiler's
# speedup vs baseline: 1.0086x; 1.0086x over previous
.LBB0_125:
	v_add_u32_e32 v178, s42, v164
	v_ashrrev_i32_e32 v179, 31, v178
	v_lshlrev_b64 v[178:179], 12, v[178:179]
	v_lshl_add_u64 v[180:181], v[146:147], 0, v[178:179]
	global_load_dwordx2 v[174:175], v[180:181], off
	v_add3_u32 v178, v164, s42, 16
	v_ashrrev_i32_e32 v179, 31, v178
	v_lshlrev_b64 v[178:179], 12, v[178:179]
	v_lshl_add_u64 v[180:181], v[146:147], 0, v[178:179]
	global_load_dwordx2 v[176:177], v[180:181], off
	s_min_u32 s44, s42, 0x7f0
	s_add_i32 s44, s44, s43
	s_waitcnt lgkmcnt(0)
	v_pk_mul_f32 v[6:7], v[6:7], v[8:9] op_sel_hi:[1,0]
	v_pk_mul_f32 v[4:5], v[4:5], v[8:9] op_sel_hi:[1,0]
	v_pk_mul_f32 v[2:3], v[2:3], v[8:9] op_sel_hi:[1,0]
	v_pk_mul_f32 v[0:1], v[0:1], v[8:9] op_sel_hi:[1,0]
	v_pk_mul_f32 v[6:7], v[86:87], v[6:7]
	v_pk_mul_f32 v[4:5], v[84:85], v[4:5]
	v_pk_mul_f32 v[2:3], v[82:83], v[2:3]
	v_pk_mul_f32 v[0:1], v[80:81], v[0:1]
	v_cmp_gt_i32_e32 vcc, s44, v123
	s_nop 1
	v_cndmask_b32_e32 v3, 0, v3, vcc
	v_cndmask_b32_e32 v2, 0, v2, vcc
	v_cndmask_b32_e32 v1, 0, v1, vcc
	v_cndmask_b32_e32 v0, 0, v0, vcc
	v_cndmask_b32_e32 v7, 0, v7, vcc
	v_cndmask_b32_e32 v6, 0, v6, vcc
	v_cndmask_b32_e32 v5, 0, v5, vcc
	v_cndmask_b32_e32 v4, 0, v4, vcc
	v_cvt_pk_bf16_f32 v32, v4, v5
	v_cvt_pk_bf16_f32 v33, v6, v7
	v_cvt_pk_bf16_f32 v34, v0, v1
	v_cvt_pk_bf16_f32 v35, v2, v3
	v_cmp_gt_i32_e32 vcc, s44, v155
	s_nop 0
	v_mfma_f32_32x32x16_bf16 v[16:31], v[32:35], v[92:95], 0
	s_nop 0
	v_mfma_f32_32x32x16_bf16 v[0:15], v[32:35], v[96:99], 0
	s_nop 0
	v_mfma_f32_32x32x16_bf16 v[48:63], v[32:35], v[100:103], 0
	s_nop 9
	v_permlane32_swap_b32_e32 v16, v0
	v_mov_b32_e32 v169, v16
	v_permlane32_swap_b32_e32 v17, v1
	v_permlane32_swap_b32_e32 v18, v2
	s_nop 0
	v_mfma_f32_32x32x16_bf16 v[32:47], v[32:35], v[104:107], 0
	v_permlane32_swap_b32_e32 v19, v3
	v_permlane32_swap_b32_e32 v20, v4
	v_permlane32_swap_b32_e32 v21, v5
	v_permlane32_swap_b32_e32 v22, v6
	s_nop 7
	v_permlane32_swap_b32_e32 v48, v32
	v_mov_b32_e32 v168, v48
	v_pk_fma_f32 v[168:169], v[150:151], v[140:141], v[168:169] op_sel:[0,1,0] op_sel_hi:[1,0,1]
	v_permlane32_swap_b32_e32 v49, v33
	v_pk_fma_f32 v[140:141], v[152:153], v[140:141], v[168:169]
	v_mov_b32_e32 v48, v17
	v_pk_fma_f32 v[16:17], v[138:139], v[140:141], v[48:49]
	v_pk_mov_b32 v[168:169], v[140:141], v[140:141] op_sel:[1,0]
	v_pk_fma_f32 v[16:17], v[152:153], v[140:141], v[16:17] op_sel:[0,1,0] op_sel_hi:[1,0,1]
	v_cvt_pk_bf16_f32 v167, v168, v169
	v_mov_b32_e32 v168, v0
	v_mov_b32_e32 v169, v32
	v_cvt_pk_bf16_f32 v0, v16, v17
	v_add_u32_e32 v32, 0x2000, v156
	v_permlane32_swap_b32_e32 v50, v34
	ds_write2_b32 v32, v167, v0 offset0:64 offset1:132
	v_mov_b32_e32 v32, v1
	v_mov_b32_e32 v0, v18
	v_mov_b32_e32 v1, v50
	v_pk_fma_f32 v[0:1], v[138:139], v[16:17], v[0:1] op_sel:[0,1,0] op_sel_hi:[1,0,1]
	v_permlane32_swap_b32_e32 v51, v35
	v_pk_fma_f32 v[0:1], v[152:153], v[16:17], v[0:1]
	v_mov_b32_e32 v50, v19
	v_pk_fma_f32 v[18:19], v[138:139], v[0:1], v[50:51] op_sel:[0,1,0] op_sel_hi:[1,0,1]
	v_cvt_pk_bf16_f32 v48, v0, v1
	v_pk_fma_f32 v[0:1], v[152:153], v[0:1], v[18:19]
	v_mov_b32_e32 v16, v2
	v_cvt_pk_bf16_f32 v2, v0, v1
	v_add_u32_e32 v18, 0x2200, v156
	ds_write2_b32 v18, v48, v2 offset0:72 offset1:140
	v_pk_fma_f32 v[18:19], v[138:139], v[0:1], v[168:169] op_sel:[0,1,0] op_sel_hi:[1,0,1]
	v_mov_b32_e32 v17, v34
	v_pk_fma_f32 v[0:1], v[152:153], v[0:1], v[18:19]
	v_mov_b32_e32 v34, v3
	v_pk_fma_f32 v[18:19], v[138:139], v[0:1], v[32:33] op_sel:[0,1,0] op_sel_hi:[1,0,1]
	v_cvt_pk_bf16_f32 v2, v0, v1
	v_pk_fma_f32 v[0:1], v[152:153], v[0:1], v[18:19]
	v_add_u32_e32 v19, 0x2400, v156
	v_pk_fma_f32 v[16:17], v[138:139], v[0:1], v[16:17] op_sel:[0,1,0] op_sel_hi:[1,0,1]
	v_cvt_pk_bf16_f32 v18, v0, v1
	v_pk_fma_f32 v[0:1], v[152:153], v[0:1], v[16:17]
	ds_write2_b32 v19, v2, v18 offset0:80 offset1:148
	v_pk_fma_f32 v[2:3], v[138:139], v[0:1], v[34:35] op_sel:[0,1,0] op_sel_hi:[1,0,1]
	v_cvt_pk_bf16_f32 v16, v0, v1
	v_pk_fma_f32 v[0:1], v[152:153], v[0:1], v[2:3]
	v_permlane32_swap_b32_e32 v52, v36
	v_cvt_pk_bf16_f32 v2, v0, v1
	v_add_u32_e32 v3, 0x2600, v156
	ds_write2_b32 v3, v16, v2 offset0:88 offset1:156
	v_mov_b32_e32 v2, v20
	v_mov_b32_e32 v3, v52
	v_pk_fma_f32 v[2:3], v[138:139], v[0:1], v[2:3] op_sel:[0,1,0] op_sel_hi:[1,0,1]
	v_permlane32_swap_b32_e32 v53, v37
	v_pk_fma_f32 v[0:1], v[152:153], v[0:1], v[2:3]
	v_mov_b32_e32 v52, v21
	v_pk_fma_f32 v[16:17], v[138:139], v[0:1], v[52:53] op_sel:[0,1,0] op_sel_hi:[1,0,1]
	v_cvt_pk_bf16_f32 v18, v0, v1
	v_pk_fma_f32 v[0:1], v[152:153], v[0:1], v[16:17]
	v_mov_b32_e32 v2, v4
	v_cvt_pk_bf16_f32 v4, v0, v1
	v_add_u32_e32 v16, 0x2800, v156
	v_permlane32_swap_b32_e32 v54, v38
	v_mov_b32_e32 v3, v36
	ds_write2_b32 v16, v18, v4 offset0:96 offset1:164
	v_mov_b32_e32 v36, v5
	v_mov_b32_e32 v4, v22
	v_mov_b32_e32 v5, v54
	v_pk_fma_f32 v[4:5], v[138:139], v[0:1], v[4:5] op_sel:[0,1,0] op_sel_hi:[1,0,1]
	v_permlane32_swap_b32_e32 v23, v7
	v_pk_fma_f32 v[0:1], v[152:153], v[0:1], v[4:5]
	v_permlane32_swap_b32_e32 v55, v39
	v_mov_b32_e32 v54, v23
	v_pk_fma_f32 v[16:17], v[138:139], v[0:1], v[54:55] op_sel:[0,1,0] op_sel_hi:[1,0,1]
	v_cvt_pk_bf16_f32 v18, v0, v1
	v_pk_fma_f32 v[0:1], v[152:153], v[0:1], v[16:17]
	v_mov_b32_e32 v4, v6
	v_pk_fma_f32 v[2:3], v[138:139], v[0:1], v[2:3] op_sel:[0,1,0] op_sel_hi:[1,0,1]
	v_cvt_pk_bf16_f32 v6, v0, v1
	v_pk_fma_f32 v[0:1], v[152:153], v[0:1], v[2:3]
	v_add_u32_e32 v16, 0x2a00, v156
	v_pk_fma_f32 v[2:3], v[138:139], v[0:1], v[36:37] op_sel:[0,1,0] op_sel_hi:[1,0,1]
	ds_write2_b32 v16, v18, v6 offset0:104 offset1:172
	v_cvt_pk_bf16_f32 v6, v0, v1
	v_pk_fma_f32 v[0:1], v[152:153], v[0:1], v[2:3]
	v_mov_b32_e32 v5, v38
	v_cvt_pk_bf16_f32 v2, v0, v1
	v_add_u32_e32 v3, 0x2c00, v156
	ds_write2_b32 v3, v6, v2 offset0:112 offset1:180
	v_pk_fma_f32 v[2:3], v[138:139], v[0:1], v[4:5] op_sel:[0,1,0] op_sel_hi:[1,0,1]
	v_mov_b32_e32 v38, v7
	v_pk_fma_f32 v[0:1], v[152:153], v[0:1], v[2:3]
	v_permlane32_swap_b32_e32 v24, v8
	v_pk_fma_f32 v[2:3], v[138:139], v[0:1], v[38:39] op_sel:[0,1,0] op_sel_hi:[1,0,1]
	v_cvt_pk_bf16_f32 v4, v0, v1
	v_pk_fma_f32 v[16:17], v[152:153], v[0:1], v[2:3]
	v_permlane32_swap_b32_e32 v56, v40
	v_cvt_pk_bf16_f32 v0, v16, v17
	v_add_u32_e32 v1, 0x2e00, v156
	ds_write2_b32 v1, v4, v0 offset0:120 offset1:188
	v_mov_b32_e32 v0, v24
	v_mov_b32_e32 v1, v56
	v_pk_fma_f32 v[0:1], v[138:139], v[16:17], v[0:1] op_sel:[0,1,0] op_sel_hi:[1,0,1]
	v_permlane32_swap_b32_e32 v25, v9
	v_pk_fma_f32 v[0:1], v[152:153], v[16:17], v[0:1]
	v_permlane32_swap_b32_e32 v57, v41
	v_mov_b32_e32 v56, v25
	v_pk_fma_f32 v[4:5], v[138:139], v[0:1], v[56:57] op_sel:[0,1,0] op_sel_hi:[1,0,1]
	v_permlane32_swap_b32_e32 v26, v10
	v_permlane32_swap_b32_e32 v58, v42
	v_cvt_pk_bf16_f32 v6, v0, v1
	v_pk_fma_f32 v[0:1], v[152:153], v[0:1], v[4:5]
	v_mov_b32_e32 v20, v26
	v_mov_b32_e32 v21, v58
	v_permlane32_swap_b32_e32 v27, v11
	v_pk_fma_f32 v[20:21], v[138:139], v[0:1], v[20:21] op_sel:[0,1,0] op_sel_hi:[1,0,1]
	v_cvt_pk_bf16_f32 v4, v0, v1
	v_permlane32_swap_b32_e32 v59, v43
	v_pk_fma_f32 v[0:1], v[152:153], v[0:1], v[20:21]
	v_mov_b32_e32 v58, v27
	v_pk_fma_f32 v[20:21], v[138:139], v[0:1], v[58:59] op_sel:[0,1,0] op_sel_hi:[1,0,1]
	v_mov_b32_e32 v2, v8
	v_mov_b32_e32 v3, v40
	v_cvt_pk_bf16_f32 v22, v0, v1
	v_pk_fma_f32 v[0:1], v[152:153], v[0:1], v[20:21]
	v_mov_b32_e32 v40, v9
	v_pk_fma_f32 v[2:3], v[138:139], v[0:1], v[2:3] op_sel:[0,1,0] op_sel_hi:[1,0,1]
	v_cvt_pk_bf16_f32 v20, v0, v1
	v_pk_fma_f32 v[0:1], v[152:153], v[0:1], v[2:3]
	v_add_u32_e32 v21, 0x3400, v156
	v_pk_fma_f32 v[2:3], v[138:139], v[0:1], v[40:41] op_sel:[0,1,0] op_sel_hi:[1,0,1]
	ds_write2_b32 v21, v22, v20 offset0:8 offset1:76
	v_cvt_pk_bf16_f32 v20, v0, v1
	v_pk_fma_f32 v[0:1], v[152:153], v[0:1], v[2:3]
	v_mov_b32_e32 v3, v42
	v_cvt_pk_bf16_f32 v2, v0, v1
	ds_write2_b32 v21, v20, v2 offset0:144 offset1:212
	v_mov_b32_e32 v2, v10
	v_pk_fma_f32 v[2:3], v[138:139], v[0:1], v[2:3] op_sel:[0,1,0] op_sel_hi:[1,0,1]
	v_mov_b32_e32 v10, v43
	v_pk_fma_f32 v[0:1], v[152:153], v[0:1], v[2:3]
	v_add_u32_e32 v5, 0x3000, v156
	v_pk_fma_f32 v[2:3], v[150:151], v[0:1], v[10:11]
	v_cvt_pk_bf16_f32 v20, v0, v1
	v_pk_fma_f32 v[0:1], v[152:153], v[0:1], v[2:3] op_sel:[0,1,0] op_sel_hi:[1,0,1]
	v_permlane32_swap_b32_e32 v28, v12
	v_permlane32_swap_b32_e32 v60, v44
	v_pk_mov_b32 v[2:3], v[0:1], v[0:1] op_sel:[1,0]
	ds_write2_b32 v5, v6, v4 offset0:128 offset1:196
	v_mov_b32_e32 v4, v60
	v_mov_b32_e32 v5, v28
	v_cvt_pk_bf16_f32 v2, v2, v3
	v_add_u32_e32 v10, 0x3800, v156
	ds_write2_b32 v10, v20, v2 offset0:24 offset1:92
	v_pk_fma_f32 v[2:3], v[150:151], v[0:1], v[4:5] op_sel:[0,1,0] op_sel_hi:[1,0,1]
	v_permlane32_swap_b32_e32 v61, v45
	v_pk_fma_f32 v[0:1], v[152:153], v[0:1], v[2:3]
	v_permlane32_swap_b32_e32 v29, v13
	v_mov_b32_e32 v28, v61
	v_pk_mov_b32 v[2:3], v[0:1], v[0:1] op_sel:[1,0]
	v_permlane32_swap_b32_e32 v30, v14
	v_cvt_pk_bf16_f32 v4, v2, v3
	v_pk_fma_f32 v[2:3], v[150:151], v[0:1], v[28:29] op_sel:[0,1,0] op_sel_hi:[1,0,1]
	v_permlane32_swap_b32_e32 v62, v46
	v_pk_fma_f32 v[0:1], v[152:153], v[0:1], v[2:3]
	v_mov_b32_e32 v8, v62
	v_pk_mov_b32 v[2:3], v[0:1], v[0:1] op_sel:[1,0]
	v_mov_b32_e32 v9, v30
	v_cvt_pk_bf16_f32 v2, v2, v3
	ds_write2_b32 v10, v4, v2 offset0:160 offset1:228
	v_pk_fma_f32 v[2:3], v[150:151], v[0:1], v[8:9] op_sel:[0,1,0] op_sel_hi:[1,0,1]
	v_permlane32_swap_b32_e32 v63, v47
	v_pk_fma_f32 v[0:1], v[152:153], v[0:1], v[2:3]
	v_permlane32_swap_b32_e32 v31, v15
	v_mov_b32_e32 v30, v63
	v_pk_mov_b32 v[2:3], v[0:1], v[0:1] op_sel:[1,0]
	v_mov_b32_e32 v6, v44
	v_cvt_pk_bf16_f32 v4, v2, v3
	v_pk_fma_f32 v[2:3], v[150:151], v[0:1], v[30:31] op_sel:[0,1,0] op_sel_hi:[1,0,1]
	v_mov_b32_e32 v7, v12
	v_pk_fma_f32 v[0:1], v[152:153], v[0:1], v[2:3]
	v_add_u32_e32 v5, 0x3c00, v156
	v_pk_mov_b32 v[2:3], v[0:1], v[0:1] op_sel:[1,0]
	v_mov_b32_e32 v12, v45
	v_cvt_pk_bf16_f32 v2, v2, v3
	ds_write2_b32 v5, v4, v2 offset0:40 offset1:108
	v_pk_fma_f32 v[2:3], v[150:151], v[0:1], v[6:7] op_sel:[0,1,0] op_sel_hi:[1,0,1]
	v_mov_b32_e32 v18, v46
	v_pk_fma_f32 v[0:1], v[152:153], v[0:1], v[2:3]
	v_mov_b32_e32 v19, v14
	v_pk_mov_b32 v[2:3], v[0:1], v[0:1] op_sel:[1,0]
	v_mov_b32_e32 v14, v47
	v_cvt_pk_bf16_f32 v4, v2, v3
	v_pk_fma_f32 v[2:3], v[150:151], v[0:1], v[12:13] op_sel:[0,1,0] op_sel_hi:[1,0,1]
	v_add_u32_e32 v6, v157, v158
	v_pk_fma_f32 v[0:1], v[152:153], v[0:1], v[2:3]
	s_nop 0
	v_pk_mov_b32 v[2:3], v[0:1], v[0:1] op_sel:[1,0]
	s_nop 0
	v_cvt_pk_bf16_f32 v2, v2, v3
	ds_write2_b32 v5, v4, v2 offset0:176 offset1:244
	v_pk_fma_f32 v[2:3], v[150:151], v[0:1], v[18:19] op_sel:[0,1,0] op_sel_hi:[1,0,1]
	s_nop 0
	v_pk_fma_f32 v[0:1], v[152:153], v[0:1], v[2:3]
	s_nop 0
	v_pk_mov_b32 v[2:3], v[0:1], v[0:1] op_sel:[1,0]
	s_nop 0
	v_cvt_pk_bf16_f32 v4, v2, v3
	v_pk_fma_f32 v[2:3], v[150:151], v[0:1], v[14:15] op_sel:[0,1,0] op_sel_hi:[1,0,1]
	s_nop 0
	v_pk_fma_f32 v[140:141], v[152:153], v[0:1], v[2:3]
	s_nop 0
	v_pk_mov_b32 v[0:1], v[140:141], v[140:141] op_sel:[1,0]
	s_nop 0
	v_cvt_pk_bf16_f32 v0, v0, v1
	v_add_u32_e32 v1, 0x4000, v156
	ds_write2_b32 v1, v4, v0 offset0:56 offset1:124
	s_waitcnt lgkmcnt(0)
	ds_read_b128 v[0:3], v6 offset:8448
	ds_read_b128 v[8:11], v6 offset:8512
	s_waitcnt lgkmcnt(1)
	v_mfma_f32_16x16x32_bf16 v[0:3], v[64:67], v[0:3], 0
	s_waitcnt lgkmcnt(0)
	v_mfma_f32_16x16x32_bf16 v[0:3], v[68:71], v[8:11], v[0:3]
	ds_read_b128 v[8:11], v6 offset:8576
	ds_read_b128 v[12:15], v6 offset:8640
	s_waitcnt lgkmcnt(1)
	v_mfma_f32_16x16x32_bf16 v[0:3], v[72:75], v[8:11], v[0:3]
	s_waitcnt lgkmcnt(0)
	v_mfma_f32_16x16x32_bf16 v[0:3], v[76:79], v[12:15], v[0:3]
	s_and_saveexec_b64 s[78:79], vcc
	s_cbranch_execz .LBB0_127
	v_add_u32_e32 v4, s42, v164
	v_ashrrev_i32_e32 v5, 31, v4
	v_lshlrev_b64 v[4:5], 12, v[4:5]
	ds_read_b32 v8, v165
	s_waitcnt vmcnt(1)
	v_lshlrev_b32_e32 v12, 16, v174
	v_and_b32_e32 v13, 0xffff0000, v174
	v_lshlrev_b32_e32 v10, 16, v175
	v_and_b32_e32 v11, 0xffff0000, v175
	s_waitcnt lgkmcnt(0)
	v_pk_mul_f32 v[14:15], v[8:9], v[10:11] op_sel_hi:[0,1]
	v_pk_mul_f32 v[12:13], v[8:9], v[12:13] op_sel_hi:[0,1]
	s_nop 0
	v_pk_mul_f32 v[8:9], v[182:183], v[12:13]
	s_nop 0
	v_pk_fma_f32 v[0:1], v[88:89], v[8:9], v[0:1]
	v_pk_mul_f32 v[10:11], v[184:185], v[14:15]
	v_mul_f32_e32 v7, 0x3d372713, v0
	v_mul_f32_e32 v7, v0, v7
	v_fma_f32 v7, v0, v7, v0
	v_mul_f32_e32 v7, 0xbfcc422a, v7
	v_mul_f32_e32 v7, 0x3fb8aa3b, v7
	v_exp_f32_e32 v7, v7
	v_pk_fma_f32 v[2:3], v[90:91], v[10:11], v[2:3]
	v_add_f32_e32 v7, 1.0, v7
	v_rcp_f32_e32 v8, v7
	v_mul_f32_e32 v7, 0x3d372713, v1
	v_mul_f32_e32 v7, v1, v7
	v_fma_f32 v7, v1, v7, v1
	v_mul_f32_e32 v7, 0xbfcc422a, v7
	v_mul_f32_e32 v7, 0x3fb8aa3b, v7
	v_exp_f32_e32 v7, v7
	s_nop 0
	v_add_f32_e32 v7, 1.0, v7
	v_rcp_f32_e32 v9, v7
	v_mul_f32_e32 v7, 0x3d372713, v2
	v_mul_f32_e32 v7, v2, v7
	v_fma_f32 v7, v2, v7, v2
	v_mul_f32_e32 v7, 0xbfcc422a, v7
	v_mul_f32_e32 v7, 0x3fb8aa3b, v7
	v_exp_f32_e32 v7, v7
	v_pk_mul_f32 v[0:1], v[0:1], v[8:9]
	v_add_f32_e32 v7, 1.0, v7
	v_rcp_f32_e32 v8, v7
	v_mul_f32_e32 v7, 0x3d372713, v3
	v_mul_f32_e32 v7, v3, v7
	v_fma_f32 v7, v3, v7, v3
	v_mul_f32_e32 v7, 0xbfcc422a, v7
	v_mul_f32_e32 v7, 0x3fb8aa3b, v7
	v_exp_f32_e32 v7, v7
	v_cvt_pk_bf16_f32 v0, v0, v1
	v_add_f32_e32 v7, 1.0, v7
	v_rcp_f32_e32 v9, v7
	s_nop 0
	v_pk_mul_f32 v[2:3], v[2:3], v[8:9]
	s_nop 0
	v_cvt_pk_bf16_f32 v1, v2, v3
	v_lshl_add_u64 v[2:3], v[142:143], 0, v[4:5]
	global_store_dwordx2 v[2:3], v[0:1], off
